# accumulator zero-init before each unit's K-loop: 128 v_mov_b32 -> 64 v_mov_b64
# speedup vs baseline: 1.0025x; 1.0025x over previous
; template <class Epi>
; __device__ __forceinline__ void gemm_phase(LAS unsigned char* lds, const Gemm g, const StaticOrder& S, const Epi& E, const int tid) {
;     ...
;         const bool has_next = S.next(ui + 1, nxt);
;         const char* nA = has_next ? (const char*)g.A + (size_t)nxt.pm * tstep : cA; const char* nB = has_next ? (const char*)g.Bt + (size_t)nxt.pn * tstep : cB;
;     ...
; #pragma unroll
;         for (int a = 0; a < 2; ++a)
; #pragma unroll
;             for (int b = 0; b < 2; ++b)
; #pragma unroll
;                 for (int m = 0; m < 4; ++m)
; #pragma unroll
;                     for (int n = 0; n < 2; ++n) acc[a][b][m][n] = (f32x4){0.f, 0.f, 0.f, 0.f};
.LBB0_125:
	s_ashr_i32 s17, s16, 31
	s_lshl_b64 s[18:19], s[16:17], 22
	v_readlane_b32 s20, v251, 43
	v_readlane_b32 s21, v251, 44
	s_add_u32 s18, s20, s18
	s_addc_u32 s19, s21, s19
	s_and_b64 s[20:21], s[22:23], exec
	s_cselect_b32 s17, s19, s31
	s_cselect_b32 s27, s18, s30
	s_ashr_i32 s15, s14, 31
	s_lshl_b64 s[20:21], s[14:15], 22
	v_readlane_b32 s34, v251, 41
	v_readlane_b32 s35, v251, 42
	s_add_u32 s20, s34, s20
	s_addc_u32 s21, s35, s21
	s_and_b64 s[34:35], s[22:23], exec
	s_cselect_b32 s15, s21, s29
	s_cselect_b32 s33, s20, s28
	s_add_u32 s49, s28, 0x100
	s_addc_u32 s50, s29, 0
	s_add_u32 s28, s30, 0x200080
	v_mov_b64_e32 v[2:3], 0
	v_mov_b64_e32 v[4:5], 0
	v_mov_b64_e32 v[6:7], 0
	v_mov_b64_e32 v[8:9], 0
	v_mov_b64_e32 v[10:11], 0
	v_mov_b64_e32 v[12:13], 0
	v_mov_b64_e32 v[14:15], 0
	v_mov_b64_e32 v[16:17], 0
	v_mov_b64_e32 v[34:35], 0
	v_mov_b64_e32 v[36:37], 0
	v_mov_b64_e32 v[38:39], 0
	v_mov_b64_e32 v[40:41], 0
	v_mov_b64_e32 v[58:59], 0
	v_mov_b64_e32 v[60:61], 0
	v_mov_b64_e32 v[62:63], 0
	v_mov_b64_e32 v[64:65], 0
	v_mov_b64_e32 v[66:67], 0
	v_mov_b64_e32 v[68:69], 0
	v_mov_b64_e32 v[70:71], 0
	v_mov_b64_e32 v[72:73], 0
	v_mov_b64_e32 v[74:75], 0
	v_mov_b64_e32 v[76:77], 0
	v_mov_b64_e32 v[78:79], 0
	v_mov_b64_e32 v[80:81], 0
	v_mov_b64_e32 v[82:83], 0
	v_mov_b64_e32 v[84:85], 0
	v_mov_b64_e32 v[86:87], 0
	v_mov_b64_e32 v[88:89], 0
	v_mov_b64_e32 v[90:91], 0
	v_mov_b64_e32 v[92:93], 0
	v_mov_b64_e32 v[94:95], 0
	v_mov_b64_e32 v[96:97], 0
	v_mov_b64_e32 v[98:99], 0
	v_mov_b64_e32 v[100:101], 0
	v_mov_b64_e32 v[102:103], 0
	v_mov_b64_e32 v[104:105], 0
	v_mov_b64_e32 v[106:107], 0
	v_mov_b64_e32 v[108:109], 0
	v_mov_b64_e32 v[110:111], 0
	v_mov_b64_e32 v[112:113], 0
	v_mov_b64_e32 v[114:115], 0
	v_mov_b64_e32 v[116:117], 0
	v_mov_b64_e32 v[118:119], 0
	v_mov_b64_e32 v[120:121], 0
	v_mov_b64_e32 v[122:123], 0
	v_mov_b64_e32 v[124:125], 0
	v_mov_b64_e32 v[126:127], 0
	v_mov_b64_e32 v[128:129], 0
	v_mov_b64_e32 v[130:131], 0
	v_mov_b64_e32 v[132:133], 0
	v_mov_b64_e32 v[134:135], 0
	v_mov_b64_e32 v[136:137], 0
	v_mov_b64_e32 v[138:139], 0
	v_mov_b64_e32 v[140:141], 0
	v_mov_b64_e32 v[142:143], 0
	v_mov_b64_e32 v[144:145], 0
	v_mov_b64_e32 v[146:147], 0
	v_mov_b64_e32 v[148:149], 0
	v_mov_b64_e32 v[150:151], 0
	v_mov_b64_e32 v[152:153], 0
	v_mov_b64_e32 v[154:155], 0
	v_mov_b64_e32 v[156:157], 0
	v_mov_b64_e32 v[158:159], 0
	v_mov_b64_e32 v[160:161], 0
	s_addc_u32 s29, s31, 0
	s_mov_b32 s51, -2
	s_waitcnt lgkmcnt(0)

; template <class Epi>
; __device__ __forceinline__ void gemm_phase(LAS unsigned char* lds, const Gemm g, const StaticOrder& S, const Epi& E, const int tid) {
;     ...
;         const bool has_next = S.next(ui + 1, nxt);
;         const char* nA = has_next ? (const char*)g.A + (size_t)nxt.pm * tstep : cA; const char* nB = has_next ? (const char*)g.Bt + (size_t)nxt.pn * tstep : cB;
;     ...
; #pragma unroll
;         for (int a = 0; a < 2; ++a)
; #pragma unroll
;             for (int b = 0; b < 2; ++b)
; #pragma unroll
;                 for (int m = 0; m < 4; ++m)
; #pragma unroll
;                     for (int n = 0; n < 2; ++n) acc[a][b][m][n] = (f32x4){0.f, 0.f, 0.f, 0.f};
.LBB0_172:
	s_ashr_i32 s17, s16, 31
	s_lshl_b64 s[18:19], s[16:17], 20
	v_readlane_b32 s20, v251, 31
	v_readlane_b32 s21, v251, 32
	s_add_u32 s18, s20, s18
	s_addc_u32 s19, s21, s19
	s_and_b64 s[20:21], s[22:23], exec
	s_cselect_b32 s17, s19, s29
	s_cselect_b32 s42, s18, s28
	s_ashr_i32 s15, s14, 31
	s_lshl_b64 s[20:21], s[14:15], 20
	s_add_u32 s20, s8, s20
	s_addc_u32 s21, s9, s21
	s_and_b64 s[30:31], s[22:23], exec
	s_cselect_b32 s15, s21, s27
	s_cselect_b32 s43, s20, s26
	s_add_u32 s44, s26, 0x100
	s_addc_u32 s45, s27, 0
	s_add_u32 s26, s28, 0x80080
	v_mov_b64_e32 v[2:3], 0
	v_mov_b64_e32 v[4:5], 0
	v_mov_b64_e32 v[6:7], 0
	v_mov_b64_e32 v[8:9], 0
	v_mov_b64_e32 v[10:11], 0
	v_mov_b64_e32 v[12:13], 0
	v_mov_b64_e32 v[14:15], 0
	v_mov_b64_e32 v[16:17], 0
	v_mov_b64_e32 v[18:19], 0
	v_mov_b64_e32 v[20:21], 0
	v_mov_b64_e32 v[22:23], 0
	v_mov_b64_e32 v[24:25], 0
	v_mov_b64_e32 v[26:27], 0
	v_mov_b64_e32 v[28:29], 0
	v_mov_b64_e32 v[30:31], 0
	v_mov_b64_e32 v[32:33], 0
	v_mov_b64_e32 v[34:35], 0
	v_mov_b64_e32 v[36:37], 0
	v_mov_b64_e32 v[38:39], 0
	v_mov_b64_e32 v[40:41], 0
	v_mov_b64_e32 v[42:43], 0
	v_mov_b64_e32 v[44:45], 0
	v_mov_b64_e32 v[46:47], 0
	v_mov_b64_e32 v[48:49], 0
	v_mov_b64_e32 v[50:51], 0
	v_mov_b64_e32 v[52:53], 0
	v_mov_b64_e32 v[54:55], 0
	v_mov_b64_e32 v[56:57], 0
	v_mov_b64_e32 v[58:59], 0
	v_mov_b64_e32 v[60:61], 0
	v_mov_b64_e32 v[62:63], 0
	v_mov_b64_e32 v[64:65], 0
	v_mov_b64_e32 v[66:67], 0
	v_mov_b64_e32 v[68:69], 0
	v_mov_b64_e32 v[70:71], 0
	v_mov_b64_e32 v[72:73], 0
	v_mov_b64_e32 v[74:75], 0
	v_mov_b64_e32 v[76:77], 0
	v_mov_b64_e32 v[78:79], 0
	v_mov_b64_e32 v[80:81], 0
	v_mov_b64_e32 v[82:83], 0
	v_mov_b64_e32 v[84:85], 0
	v_mov_b64_e32 v[86:87], 0
	v_mov_b64_e32 v[88:89], 0
	v_mov_b64_e32 v[90:91], 0
	v_mov_b64_e32 v[92:93], 0
	v_mov_b64_e32 v[94:95], 0
	v_mov_b64_e32 v[96:97], 0
	v_mov_b64_e32 v[98:99], 0
	v_mov_b64_e32 v[100:101], 0
	v_mov_b64_e32 v[102:103], 0
	v_mov_b64_e32 v[104:105], 0
	v_mov_b64_e32 v[106:107], 0
	v_mov_b64_e32 v[108:109], 0
	v_mov_b64_e32 v[110:111], 0
	v_mov_b64_e32 v[112:113], 0
	v_mov_b64_e32 v[114:115], 0
	v_mov_b64_e32 v[116:117], 0
	v_mov_b64_e32 v[118:119], 0
	v_mov_b64_e32 v[120:121], 0
	v_mov_b64_e32 v[122:123], 0
	v_mov_b64_e32 v[124:125], 0
	v_mov_b64_e32 v[126:127], 0
	v_mov_b64_e32 v[128:129], 0
	s_addc_u32 s27, s29, 0
	s_mov_b32 s46, -2

; template <class Epi>
; __device__ __forceinline__ void gemm_phase(LAS unsigned char* lds, const Gemm g, const StaticOrder& S, const Epi& E, const int tid) {
;     ...
;         const bool has_next = S.next(ui + 1, nxt);
;         const char* nA = has_next ? (const char*)g.A + (size_t)nxt.pm * tstep : cA; const char* nB = has_next ? (const char*)g.Bt + (size_t)nxt.pn * tstep : cB;
;     ...
; #pragma unroll
;         for (int a = 0; a < 2; ++a)
; #pragma unroll
;             for (int b = 0; b < 2; ++b)
; #pragma unroll
;                 for (int m = 0; m < 4; ++m)
; #pragma unroll
;                     for (int n = 0; n < 2; ++n) acc[a][b][m][n] = (f32x4){0.f, 0.f, 0.f, 0.f};
.LBB0_205:
	s_ashr_i32 s17, s16, 31
	s_lshl_b64 s[18:19], s[16:17], 18
	v_readlane_b32 s20, v251, 47
	v_readlane_b32 s21, v251, 48
	s_add_u32 s18, s20, s18
	s_addc_u32 s19, s21, s19
	s_and_b64 s[20:21], s[22:23], exec
	s_cselect_b32 s17, s19, s31
	s_cselect_b32 s27, s18, s30
	s_ashr_i32 s15, s14, 31
	s_lshl_b64 s[20:21], s[14:15], 18
	v_readlane_b32 s34, v251, 39
	v_readlane_b32 s35, v251, 40
	s_add_u32 s20, s34, s20
	s_addc_u32 s21, s35, s21
	s_and_b64 s[34:35], s[22:23], exec
	s_cselect_b32 s15, s21, s29
	s_cselect_b32 s33, s20, s28
	s_add_u32 s49, s28, 0x100
	s_addc_u32 s50, s29, 0
	s_add_u32 s28, s30, 0x20080
	v_mov_b64_e32 v[2:3], 0
	v_mov_b64_e32 v[4:5], 0
	v_mov_b64_e32 v[6:7], 0
	v_mov_b64_e32 v[8:9], 0
	v_mov_b64_e32 v[10:11], 0
	v_mov_b64_e32 v[12:13], 0
	v_mov_b64_e32 v[14:15], 0
	v_mov_b64_e32 v[16:17], 0
	v_mov_b64_e32 v[34:35], 0
	v_mov_b64_e32 v[36:37], 0
	v_mov_b64_e32 v[38:39], 0
	v_mov_b64_e32 v[40:41], 0
	v_mov_b64_e32 v[58:59], 0
	v_mov_b64_e32 v[60:61], 0
	v_mov_b64_e32 v[62:63], 0
	v_mov_b64_e32 v[64:65], 0
	v_mov_b64_e32 v[66:67], 0
	v_mov_b64_e32 v[68:69], 0
	v_mov_b64_e32 v[70:71], 0
	v_mov_b64_e32 v[72:73], 0
	v_mov_b64_e32 v[74:75], 0
	v_mov_b64_e32 v[76:77], 0
	v_mov_b64_e32 v[78:79], 0
	v_mov_b64_e32 v[80:81], 0
	v_mov_b64_e32 v[82:83], 0
	v_mov_b64_e32 v[84:85], 0
	v_mov_b64_e32 v[86:87], 0
	v_mov_b64_e32 v[88:89], 0
	v_mov_b64_e32 v[90:91], 0
	v_mov_b64_e32 v[92:93], 0
	v_mov_b64_e32 v[94:95], 0
	v_mov_b64_e32 v[96:97], 0
	v_mov_b64_e32 v[98:99], 0
	v_mov_b64_e32 v[100:101], 0
	v_mov_b64_e32 v[102:103], 0
	v_mov_b64_e32 v[104:105], 0
	v_mov_b64_e32 v[106:107], 0
	v_mov_b64_e32 v[108:109], 0
	v_mov_b64_e32 v[110:111], 0
	v_mov_b64_e32 v[112:113], 0
	v_mov_b64_e32 v[114:115], 0
	v_mov_b64_e32 v[116:117], 0
	v_mov_b64_e32 v[118:119], 0
	v_mov_b64_e32 v[120:121], 0
	v_mov_b64_e32 v[122:123], 0
	v_mov_b64_e32 v[124:125], 0
	v_mov_b64_e32 v[126:127], 0
	v_mov_b64_e32 v[128:129], 0
	v_mov_b64_e32 v[130:131], 0
	v_mov_b64_e32 v[132:133], 0
	v_mov_b64_e32 v[134:135], 0
	v_mov_b64_e32 v[136:137], 0
	v_mov_b64_e32 v[138:139], 0
	v_mov_b64_e32 v[140:141], 0
	v_mov_b64_e32 v[142:143], 0
	v_mov_b64_e32 v[144:145], 0
	v_mov_b64_e32 v[146:147], 0
	v_mov_b64_e32 v[148:149], 0
	v_mov_b64_e32 v[150:151], 0
	v_mov_b64_e32 v[152:153], 0
	v_mov_b64_e32 v[154:155], 0
	v_mov_b64_e32 v[156:157], 0
	v_mov_b64_e32 v[158:159], 0
	v_mov_b64_e32 v[160:161], 0
	s_addc_u32 s29, s31, 0
	s_mov_b32 s51, -2
	s_waitcnt lgkmcnt(0)

; template <class Epi>
; __device__ __forceinline__ void gemm_phase(LAS unsigned char* lds, const Gemm g, const StaticOrder& S, const Epi& E, const int tid) {
;     ...
;         const bool has_next = S.next(ui + 1, nxt);
;         const char* nA = has_next ? (const char*)g.A + (size_t)nxt.pm * tstep : cA; const char* nB = has_next ? (const char*)g.Bt + (size_t)nxt.pn * tstep : cB;
;     ...
; #pragma unroll
;         for (int a = 0; a < 2; ++a)
; #pragma unroll
;             for (int b = 0; b < 2; ++b)
; #pragma unroll
;                 for (int m = 0; m < 4; ++m)
; #pragma unroll
;                     for (int n = 0; n < 2; ++n) acc[a][b][m][n] = (f32x4){0.f, 0.f, 0.f, 0.f};
.LBB0_260:
	s_ashr_i32 s19, s18, 31
	s_lshl_b64 s[20:21], s[18:19], 20
	v_readlane_b32 s22, v251, 31
	v_readlane_b32 s23, v251, 32
	s_add_u32 s20, s22, s20
	s_addc_u32 s21, s23, s21
	s_and_b64 s[22:23], s[24:25], exec
	s_cselect_b32 s19, s21, s31
	s_cselect_b32 s44, s20, s30
	s_ashr_i32 s17, s16, 31
	s_lshl_b64 s[22:23], s[16:17], 20
	v_readlane_b32 s34, v251, 37
	v_readlane_b32 s35, v251, 38
	s_add_u32 s22, s34, s22
	s_addc_u32 s23, s35, s23
	s_and_b64 s[34:35], s[24:25], exec
	s_cselect_b32 s17, s23, s29
	s_cselect_b32 s45, s22, s28
	s_add_u32 s46, s28, 0x100
	s_addc_u32 s47, s29, 0
	s_add_u32 s28, s30, 0x80080
	v_mov_b64_e32 v[2:3], 0
	v_mov_b64_e32 v[4:5], 0
	v_mov_b64_e32 v[6:7], 0
	v_mov_b64_e32 v[8:9], 0
	v_mov_b64_e32 v[10:11], 0
	v_mov_b64_e32 v[12:13], 0
	v_mov_b64_e32 v[14:15], 0
	v_mov_b64_e32 v[16:17], 0
	v_mov_b64_e32 v[18:19], 0
	v_mov_b64_e32 v[20:21], 0
	v_mov_b64_e32 v[22:23], 0
	v_mov_b64_e32 v[24:25], 0
	v_mov_b64_e32 v[26:27], 0
	v_mov_b64_e32 v[28:29], 0
	v_mov_b64_e32 v[30:31], 0
	v_mov_b64_e32 v[32:33], 0
	v_mov_b64_e32 v[34:35], 0
	v_mov_b64_e32 v[36:37], 0
	v_mov_b64_e32 v[38:39], 0
	v_mov_b64_e32 v[40:41], 0
	v_mov_b64_e32 v[42:43], 0
	v_mov_b64_e32 v[44:45], 0
	v_mov_b64_e32 v[46:47], 0
	v_mov_b64_e32 v[48:49], 0
	v_mov_b64_e32 v[50:51], 0
	v_mov_b64_e32 v[52:53], 0
	v_mov_b64_e32 v[54:55], 0
	v_mov_b64_e32 v[56:57], 0
	v_mov_b64_e32 v[58:59], 0
	v_mov_b64_e32 v[60:61], 0
	v_mov_b64_e32 v[62:63], 0
	v_mov_b64_e32 v[64:65], 0
	v_mov_b64_e32 v[66:67], 0
	v_mov_b64_e32 v[68:69], 0
	v_mov_b64_e32 v[70:71], 0
	v_mov_b64_e32 v[72:73], 0
	v_mov_b64_e32 v[74:75], 0
	v_mov_b64_e32 v[76:77], 0
	v_mov_b64_e32 v[78:79], 0
	v_mov_b64_e32 v[80:81], 0
	v_mov_b64_e32 v[82:83], 0
	v_mov_b64_e32 v[84:85], 0
	v_mov_b64_e32 v[86:87], 0
	v_mov_b64_e32 v[88:89], 0
	v_mov_b64_e32 v[90:91], 0
	v_mov_b64_e32 v[92:93], 0
	v_mov_b64_e32 v[94:95], 0
	v_mov_b64_e32 v[96:97], 0
	v_mov_b64_e32 v[98:99], 0
	v_mov_b64_e32 v[100:101], 0
	v_mov_b64_e32 v[102:103], 0
	v_mov_b64_e32 v[104:105], 0
	v_mov_b64_e32 v[106:107], 0
	v_mov_b64_e32 v[108:109], 0
	v_mov_b64_e32 v[110:111], 0
	v_mov_b64_e32 v[112:113], 0
	v_mov_b64_e32 v[114:115], 0
	v_mov_b64_e32 v[116:117], 0
	v_mov_b64_e32 v[118:119], 0
	v_mov_b64_e32 v[120:121], 0
	v_mov_b64_e32 v[122:123], 0
	v_mov_b64_e32 v[124:125], 0
	v_mov_b64_e32 v[126:127], 0
	v_mov_b64_e32 v[128:129], 0
	s_addc_u32 s29, s31, 0
	s_mov_b32 s48, -2

; template <class Epi>
; __device__ __forceinline__ void gemm_phase(LAS unsigned char* lds, const Gemm g, const StaticOrder& S, const Epi& E, const int tid) {
;     ...
;         const bool has_next = S.next(ui + 1, nxt);
;         const char* nA = has_next ? (const char*)g.A + (size_t)nxt.pm * tstep : cA; const char* nB = has_next ? (const char*)g.Bt + (size_t)nxt.pn * tstep : cB;
;     ...
; #pragma unroll
;         for (int a = 0; a < 2; ++a)
; #pragma unroll
;             for (int b = 0; b < 2; ++b)
; #pragma unroll
;                 for (int m = 0; m < 4; ++m)
; #pragma unroll
;                     for (int n = 0; n < 2; ++n) acc[a][b][m][n] = (f32x4){0.f, 0.f, 0.f, 0.f};
.LBB0_313:
	s_ashr_i32 s27, s26, 31
	s_lshl_b64 s[6:7], s[26:27], 20
	v_readlane_b32 s28, v251, 43
	v_readlane_b32 s29, v251, 44
	s_add_u32 s28, s28, s6
	s_addc_u32 s29, s29, s7
	s_and_b64 s[6:7], s[34:35], exec
	s_cselect_b32 s27, s29, s43
	s_cselect_b32 s39, s28, s42
	s_ashr_i32 s25, s24, 31
	s_lshl_b64 s[6:7], s[24:25], 20
	s_add_u32 s30, s52, s6
	s_addc_u32 s31, s53, s7
	s_and_b64 s[6:7], s[34:35], exec
	s_cselect_b32 s25, s31, s41
	s_cselect_b32 s52, s30, s40
	s_add_u32 s53, s40, 0x100
	s_addc_u32 s54, s41, 0
	s_add_u32 s6, s42, 0x80080
	v_mov_b64_e32 v[2:3], 0
	v_mov_b64_e32 v[4:5], 0
	v_mov_b64_e32 v[6:7], 0
	v_mov_b64_e32 v[8:9], 0
	v_mov_b64_e32 v[10:11], 0
	v_mov_b64_e32 v[12:13], 0
	v_mov_b64_e32 v[14:15], 0
	v_mov_b64_e32 v[16:17], 0
	v_mov_b64_e32 v[18:19], 0
	v_mov_b64_e32 v[20:21], 0
	v_mov_b64_e32 v[22:23], 0
	v_mov_b64_e32 v[24:25], 0
	v_mov_b64_e32 v[26:27], 0
	v_mov_b64_e32 v[28:29], 0
	v_mov_b64_e32 v[30:31], 0
	v_mov_b64_e32 v[32:33], 0
	v_mov_b64_e32 v[50:51], 0
	v_mov_b64_e32 v[52:53], 0
	v_mov_b64_e32 v[54:55], 0
	v_mov_b64_e32 v[56:57], 0
	v_mov_b64_e32 v[74:75], 0
	v_mov_b64_e32 v[76:77], 0
	v_mov_b64_e32 v[78:79], 0
	v_mov_b64_e32 v[80:81], 0
	v_mov_b64_e32 v[82:83], 0
	v_mov_b64_e32 v[84:85], 0
	v_mov_b64_e32 v[86:87], 0
	v_mov_b64_e32 v[88:89], 0
	v_mov_b64_e32 v[90:91], 0
	v_mov_b64_e32 v[92:93], 0
	v_mov_b64_e32 v[94:95], 0
	v_mov_b64_e32 v[96:97], 0
	v_mov_b64_e32 v[98:99], 0
	v_mov_b64_e32 v[100:101], 0
	v_mov_b64_e32 v[102:103], 0
	v_mov_b64_e32 v[104:105], 0
	v_mov_b64_e32 v[106:107], 0
	v_mov_b64_e32 v[108:109], 0
	v_mov_b64_e32 v[110:111], 0
	v_mov_b64_e32 v[112:113], 0
	v_mov_b64_e32 v[114:115], 0
	v_mov_b64_e32 v[116:117], 0
	v_mov_b64_e32 v[118:119], 0
	v_mov_b64_e32 v[120:121], 0
	v_mov_b64_e32 v[122:123], 0
	v_mov_b64_e32 v[124:125], 0
	v_mov_b64_e32 v[126:127], 0
	v_mov_b64_e32 v[128:129], 0
	v_mov_b64_e32 v[130:131], 0
	v_mov_b64_e32 v[132:133], 0
	v_mov_b64_e32 v[134:135], 0
	v_mov_b64_e32 v[136:137], 0
	v_mov_b64_e32 v[138:139], 0
	v_mov_b64_e32 v[140:141], 0
	v_mov_b64_e32 v[142:143], 0
	v_mov_b64_e32 v[144:145], 0
	v_mov_b64_e32 v[146:147], 0
	v_mov_b64_e32 v[148:149], 0
	v_mov_b64_e32 v[150:151], 0
	v_mov_b64_e32 v[152:153], 0
	v_mov_b64_e32 v[154:155], 0
	v_mov_b64_e32 v[156:157], 0
	v_mov_b64_e32 v[158:159], 0
	v_mov_b64_e32 v[160:161], 0
	s_addc_u32 s7, s43, 0
	s_mov_b32 s55, -2
	s_waitcnt lgkmcnt(0)

; template <class Epi>
; __device__ __forceinline__ void gemm_phase(LAS unsigned char* lds, const Gemm g, const StaticOrder& S, const Epi& E, const int tid) {
;     ...
;         const bool has_next = S.next(ui + 1, nxt);
;         const char* nA = has_next ? (const char*)g.A + (size_t)nxt.pm * tstep : cA; const char* nB = has_next ? (const char*)g.Bt + (size_t)nxt.pn * tstep : cB;
;     ...
; #pragma unroll
;         for (int a = 0; a < 2; ++a)
; #pragma unroll
;             for (int b = 0; b < 2; ++b)
; #pragma unroll
;                 for (int m = 0; m < 4; ++m)
; #pragma unroll
;                     for (int n = 0; n < 2; ++n) acc[a][b][m][n] = (f32x4){0.f, 0.f, 0.f, 0.f};
.LBB0_545:
	s_ashr_i32 s19, s18, 31
	s_lshl_b64 s[20:21], s[18:19], 20
	v_readlane_b32 s22, v251, 31
	v_readlane_b32 s23, v251, 32
	s_add_u32 s20, s22, s20
	s_addc_u32 s21, s23, s21
	s_and_b64 s[22:23], s[24:25], exec
	s_cselect_b32 s19, s21, s29
	s_cselect_b32 s31, s20, s28
	s_ashr_i32 s17, s16, 31
	s_lshl_b64 s[22:23], s[16:17], 20
	v_readlane_b32 s34, v251, 53
	v_readlane_b32 s35, v251, 54
	s_add_u32 s22, s34, s22
	s_addc_u32 s23, s35, s23
	s_and_b64 s[34:35], s[24:25], exec
	s_cselect_b32 s17, s23, s27
	s_cselect_b32 s33, s22, s26
	s_add_u32 s37, s26, 0x100
	s_addc_u32 s38, s27, 0
	s_add_u32 s26, s28, 0x80080
	v_mov_b64_e32 v[2:3], 0
	v_mov_b64_e32 v[4:5], 0
	v_mov_b64_e32 v[6:7], 0
	v_mov_b64_e32 v[8:9], 0
	v_mov_b64_e32 v[10:11], 0
	v_mov_b64_e32 v[12:13], 0
	v_mov_b64_e32 v[14:15], 0
	v_mov_b64_e32 v[16:17], 0
	v_mov_b64_e32 v[18:19], 0
	v_mov_b64_e32 v[20:21], 0
	v_mov_b64_e32 v[22:23], 0
	v_mov_b64_e32 v[24:25], 0
	v_mov_b64_e32 v[26:27], 0
	v_mov_b64_e32 v[28:29], 0
	v_mov_b64_e32 v[30:31], 0
	v_mov_b64_e32 v[32:33], 0
	v_mov_b64_e32 v[34:35], 0
	v_mov_b64_e32 v[36:37], 0
	v_mov_b64_e32 v[38:39], 0
	v_mov_b64_e32 v[40:41], 0
	v_mov_b64_e32 v[42:43], 0
	v_mov_b64_e32 v[44:45], 0
	v_mov_b64_e32 v[46:47], 0
	v_mov_b64_e32 v[48:49], 0
	v_mov_b64_e32 v[50:51], 0
	v_mov_b64_e32 v[52:53], 0
	v_mov_b64_e32 v[54:55], 0
	v_mov_b64_e32 v[56:57], 0
	v_mov_b64_e32 v[58:59], 0
	v_mov_b64_e32 v[60:61], 0
	v_mov_b64_e32 v[62:63], 0
	v_mov_b64_e32 v[64:65], 0
	v_mov_b64_e32 v[66:67], 0
	v_mov_b64_e32 v[68:69], 0
	v_mov_b64_e32 v[70:71], 0
	v_mov_b64_e32 v[72:73], 0
	v_mov_b64_e32 v[74:75], 0
	v_mov_b64_e32 v[76:77], 0
	v_mov_b64_e32 v[78:79], 0
	v_mov_b64_e32 v[80:81], 0
	v_mov_b64_e32 v[82:83], 0
	v_mov_b64_e32 v[84:85], 0
	v_mov_b64_e32 v[86:87], 0
	v_mov_b64_e32 v[88:89], 0
	v_mov_b64_e32 v[90:91], 0
	v_mov_b64_e32 v[92:93], 0
	v_mov_b64_e32 v[94:95], 0
	v_mov_b64_e32 v[96:97], 0
	v_mov_b64_e32 v[98:99], 0
	v_mov_b64_e32 v[100:101], 0
	v_mov_b64_e32 v[102:103], 0
	v_mov_b64_e32 v[104:105], 0
	v_mov_b64_e32 v[106:107], 0
	v_mov_b64_e32 v[108:109], 0
	v_mov_b64_e32 v[110:111], 0
	v_mov_b64_e32 v[112:113], 0
	v_mov_b64_e32 v[114:115], 0
	v_mov_b64_e32 v[116:117], 0
	v_mov_b64_e32 v[118:119], 0
	v_mov_b64_e32 v[120:121], 0
	v_mov_b64_e32 v[122:123], 0
	v_mov_b64_e32 v[124:125], 0
	v_mov_b64_e32 v[126:127], 0
	v_mov_b64_e32 v[128:129], 0
	s_addc_u32 s27, s29, 0
	s_mov_b32 s39, -2
	s_waitcnt lgkmcnt(0)

; template <class Epi>
; __device__ __forceinline__ void gemm_phase(LAS unsigned char* lds, const Gemm g, const StaticOrder& S, const Epi& E, const int tid) {
;     ...
;         const bool has_next = S.next(ui + 1, nxt);
;         const char* nA = has_next ? (const char*)g.A + (size_t)nxt.pm * tstep : cA; const char* nB = has_next ? (const char*)g.Bt + (size_t)nxt.pn * tstep : cB;
;     ...
; #pragma unroll
;         for (int a = 0; a < 2; ++a)
; #pragma unroll
;             for (int b = 0; b < 2; ++b)
; #pragma unroll
;                 for (int m = 0; m < 4; ++m)
; #pragma unroll
;                     for (int n = 0; n < 2; ++n) acc[a][b][m][n] = (f32x4){0.f, 0.f, 0.f, 0.f};
.LBB0_843:
	s_ashr_i32 s15, s14, 31
	s_lshl_b64 s[18:19], s[14:15], 20
	s_add_u32 s18, s2, s18
	s_addc_u32 s19, s33, s19
	s_and_b64 s[20:21], s[16:17], exec
	s_cselect_b32 s15, s19, s29
	s_cselect_b32 s43, s18, s28
	s_ashr_i32 s13, s12, 31
	s_lshl_b64 s[20:21], s[12:13], 20
	s_add_u32 s20, s8, s20
	s_addc_u32 s21, s9, s21
	s_and_b64 s[30:31], s[16:17], exec
	s_cselect_b32 s13, s21, s27
	s_cselect_b32 s44, s20, s26
	s_add_u32 s45, s26, 0x100
	s_addc_u32 s46, s27, 0
	s_add_u32 s26, s28, 0x80080
	v_mov_b64_e32 v[2:3], 0
	v_mov_b64_e32 v[4:5], 0
	v_mov_b64_e32 v[6:7], 0
	v_mov_b64_e32 v[8:9], 0
	v_mov_b64_e32 v[10:11], 0
	v_mov_b64_e32 v[12:13], 0
	v_mov_b64_e32 v[14:15], 0
	v_mov_b64_e32 v[16:17], 0
	v_mov_b64_e32 v[18:19], 0
	v_mov_b64_e32 v[20:21], 0
	v_mov_b64_e32 v[22:23], 0
	v_mov_b64_e32 v[24:25], 0
	v_mov_b64_e32 v[26:27], 0
	v_mov_b64_e32 v[28:29], 0
	v_mov_b64_e32 v[30:31], 0
	v_mov_b64_e32 v[32:33], 0
	v_mov_b64_e32 v[34:35], 0
	v_mov_b64_e32 v[36:37], 0
	v_mov_b64_e32 v[38:39], 0
	v_mov_b64_e32 v[40:41], 0
	v_mov_b64_e32 v[42:43], 0
	v_mov_b64_e32 v[44:45], 0
	v_mov_b64_e32 v[46:47], 0
	v_mov_b64_e32 v[48:49], 0
	v_mov_b64_e32 v[50:51], 0
	v_mov_b64_e32 v[52:53], 0
	v_mov_b64_e32 v[54:55], 0
	v_mov_b64_e32 v[56:57], 0
	v_mov_b64_e32 v[58:59], 0
	v_mov_b64_e32 v[60:61], 0
	v_mov_b64_e32 v[62:63], 0
	v_mov_b64_e32 v[64:65], 0
	v_mov_b64_e32 v[66:67], 0
	v_mov_b64_e32 v[68:69], 0
	v_mov_b64_e32 v[70:71], 0
	v_mov_b64_e32 v[72:73], 0
	v_mov_b64_e32 v[74:75], 0
	v_mov_b64_e32 v[76:77], 0
	v_mov_b64_e32 v[78:79], 0
	v_mov_b64_e32 v[80:81], 0
	v_mov_b64_e32 v[82:83], 0
	v_mov_b64_e32 v[84:85], 0
	v_mov_b64_e32 v[86:87], 0
	v_mov_b64_e32 v[88:89], 0
	v_mov_b64_e32 v[90:91], 0
	v_mov_b64_e32 v[92:93], 0
	v_mov_b64_e32 v[94:95], 0
	v_mov_b64_e32 v[96:97], 0
	v_mov_b64_e32 v[98:99], 0
	v_mov_b64_e32 v[100:101], 0
	v_mov_b64_e32 v[102:103], 0
	v_mov_b64_e32 v[104:105], 0
	v_mov_b64_e32 v[106:107], 0
	v_mov_b64_e32 v[108:109], 0
	v_mov_b64_e32 v[110:111], 0
	v_mov_b64_e32 v[112:113], 0
	v_mov_b64_e32 v[114:115], 0
	v_mov_b64_e32 v[116:117], 0
	v_mov_b64_e32 v[118:119], 0
	v_mov_b64_e32 v[120:121], 0
	v_mov_b64_e32 v[122:123], 0
	v_mov_b64_e32 v[124:125], 0
	v_mov_b64_e32 v[126:127], 0
	v_mov_b64_e32 v[128:129], 0
	s_addc_u32 s27, s29, 0
	s_mov_b32 s47, -2

; template <class Epi>
; __device__ __forceinline__ void gemm_phase(LAS unsigned char* lds, const Gemm g, const StaticOrder& S, const Epi& E, const int tid) {
;     ...
;         const bool has_next = S.next(ui + 1, nxt);
;         const char* nA = has_next ? (const char*)g.A + (size_t)nxt.pm * tstep : cA; const char* nB = has_next ? (const char*)g.Bt + (size_t)nxt.pn * tstep : cB;
;     ...
; #pragma unroll
;         for (int a = 0; a < 2; ++a)
; #pragma unroll
;             for (int b = 0; b < 2; ++b)
; #pragma unroll
;                 for (int m = 0; m < 4; ++m)
; #pragma unroll
;                     for (int n = 0; n < 2; ++n) acc[a][b][m][n] = (f32x4){0.f, 0.f, 0.f, 0.f};
.LBB0_860:
	s_ashr_i32 s17, s16, 31
	s_lshl_b64 s[20:21], s[16:17], 20
	s_add_u32 s20, s37, s20
	s_addc_u32 s21, s38, s21
	s_and_b64 s[22:23], s[18:19], exec
	s_cselect_b32 s17, s21, s31
	s_cselect_b32 s46, s20, s30
	s_ashr_i32 s15, s14, 31
	s_lshl_b64 s[22:23], s[14:15], 20
	s_add_u32 s22, s2, s22
	s_addc_u32 s23, s33, s23
	s_and_b64 s[34:35], s[18:19], exec
	s_cselect_b32 s15, s23, s29
	s_cselect_b32 s47, s22, s28
	s_add_u32 s48, s28, 0x100
	s_addc_u32 s49, s29, 0
	s_add_u32 s28, s30, 0x80080
	v_mov_b64_e32 v[2:3], 0
	v_mov_b64_e32 v[4:5], 0
	v_mov_b64_e32 v[6:7], 0
	v_mov_b64_e32 v[8:9], 0
	v_mov_b64_e32 v[10:11], 0
	v_mov_b64_e32 v[12:13], 0
	v_mov_b64_e32 v[14:15], 0
	v_mov_b64_e32 v[16:17], 0
	v_mov_b64_e32 v[18:19], 0
	v_mov_b64_e32 v[20:21], 0
	v_mov_b64_e32 v[22:23], 0
	v_mov_b64_e32 v[24:25], 0
	v_mov_b64_e32 v[26:27], 0
	v_mov_b64_e32 v[28:29], 0
	v_mov_b64_e32 v[30:31], 0
	v_mov_b64_e32 v[32:33], 0
	v_mov_b64_e32 v[34:35], 0
	v_mov_b64_e32 v[36:37], 0
	v_mov_b64_e32 v[38:39], 0
	v_mov_b64_e32 v[40:41], 0
	v_mov_b64_e32 v[42:43], 0
	v_mov_b64_e32 v[44:45], 0
	v_mov_b64_e32 v[46:47], 0
	v_mov_b64_e32 v[48:49], 0
	v_mov_b64_e32 v[50:51], 0
	v_mov_b64_e32 v[52:53], 0
	v_mov_b64_e32 v[54:55], 0
	v_mov_b64_e32 v[56:57], 0
	v_mov_b64_e32 v[58:59], 0
	v_mov_b64_e32 v[60:61], 0
	v_mov_b64_e32 v[62:63], 0
	v_mov_b64_e32 v[64:65], 0
	v_mov_b64_e32 v[66:67], 0
	v_mov_b64_e32 v[68:69], 0
	v_mov_b64_e32 v[70:71], 0
	v_mov_b64_e32 v[72:73], 0
	v_mov_b64_e32 v[74:75], 0
	v_mov_b64_e32 v[76:77], 0
	v_mov_b64_e32 v[78:79], 0
	v_mov_b64_e32 v[80:81], 0
	v_mov_b64_e32 v[82:83], 0
	v_mov_b64_e32 v[84:85], 0
	v_mov_b64_e32 v[86:87], 0
	v_mov_b64_e32 v[88:89], 0
	v_mov_b64_e32 v[90:91], 0
	v_mov_b64_e32 v[92:93], 0
	v_mov_b64_e32 v[94:95], 0
	v_mov_b64_e32 v[96:97], 0
	v_mov_b64_e32 v[98:99], 0
	v_mov_b64_e32 v[100:101], 0
	v_mov_b64_e32 v[102:103], 0
	v_mov_b64_e32 v[104:105], 0
	v_mov_b64_e32 v[106:107], 0
	v_mov_b64_e32 v[108:109], 0
	v_mov_b64_e32 v[110:111], 0
	v_mov_b64_e32 v[112:113], 0
	v_mov_b64_e32 v[114:115], 0
	v_mov_b64_e32 v[116:117], 0
	v_mov_b64_e32 v[118:119], 0
	v_mov_b64_e32 v[120:121], 0
	v_mov_b64_e32 v[122:123], 0
	v_mov_b64_e32 v[124:125], 0
	v_mov_b64_e32 v[126:127], 0
	v_mov_b64_e32 v[128:129], 0
	s_addc_u32 s29, s31, 0
	s_mov_b32 s50, -2
